# cross-attention epilogue: permlane16_swap pairs and 8 dwordx4 stores instead of 16 dwordx2
# baseline (speedup 1.0000x reference)
; __device__ __forceinline__ void phase_xattn(CArgs& A, int l, unsigned char* lds, int tid) {
;     ...
;         for (int kt = 0; kt < 4; ++kt) {
;             __syncthreads();
; #pragma unroll
;             for (int i = 0; i < 4; ++i) *(u32x4*)(Ks + skey * XA_KP + (sdc + i * 8) * 2) = kr[i];
; #pragma unroll
;             for (int i = 0; i < 4; ++i) *(u32x4*)(Vt + skey * XA_VP + (sdc + i * 8) * 2) = vr[i];
;             __syncthreads();
;             if (kt + 1 < 4) {
; #pragma unroll
;                 for (int i = 0; i < 4; ++i) { kr[i] = *(const u32x4*)(kvbase + (size_t)(kt + 1) * 64 * 4096 + i * 8); vr[i] = *(const u32x4*)(kvbase + (size_t)(kt + 1) * 64 * 4096 + 1024 + i * 8); } }
;             f32x4 sc[4];
; #pragma unroll
;             for (int blk = 0; blk < 4; ++blk) { sc[blk] = (f32x4){0.f, 0.f, 0.f, 0.f};
; #pragma unroll
;                 for (int ks = 0; ks < 8; ++ks) { const bf16x8 a = *(const bf16x8*)(Ks + (blk * 16 + r) * XA_KP + (32 * ks + 8 * g) * 2);
;                     sc[blk] = __builtin_amdgcn_mfma_f32_16x16x32_bf16(a, qf[ks], sc[blk], 0, 0, 0); } }
;             float mx = -INFINITY;
; #pragma unroll
;             for (int blk = 0; blk < 4; ++blk)
; #pragma unroll
;                 for (int e = 0; e < 4; ++e) { sc[blk][e] *= LOG2E; mx = fmaxf(mx, sc[blk][e]); }
;             mx = fmaxf(mx, __shfl_xor(mx, 16)); mx = fmaxf(mx, __shfl_xor(mx, 32));
.LBB0_145:
	v_add_u32_e32 v157, v154, v146
	s_barrier
	s_waitcnt vmcnt(4)
	ds_write_b128 v157, v[110:113]
	ds_write_b128 v157, v[106:109] offset:16
	ds_write_b128 v157, v[102:105] offset:32
	ds_write_b128 v157, v[98:101] offset:48
	s_waitcnt vmcnt(0)
	ds_write_b128 v155, v[126:129] offset:34816
	ds_write_b128 v155, v[122:125] offset:34832
	ds_write_b128 v155, v[118:121] offset:34848
	ds_write_b128 v155, v[114:117] offset:34864
	v_lshl_add_u64 v[126:127], v[148:149], 0, s[44:45]
	v_mov_b32_e32 v158, v130
	s_waitcnt lgkmcnt(0)
	s_barrier
	ds_read_b128 v[204:207], v153
	ds_read_b128 v[208:211], v153 offset:64
	ds_read_b128 v[212:215], v153 offset:128
	ds_read_b128 v[216:219], v153 offset:192
	ds_read_b128 v[220:223], v153 offset:256
	ds_read_b128 v[224:227], v153 offset:320
	ds_read_b128 v[228:231], v153 offset:384
	ds_read_b128 v[232:235], v153 offset:448
	ds_read_b128 v[236:239], v153 offset:8704
	ds_read_b128 v[240:243], v153 offset:8768
	ds_read_b128 v[244:247], v153 offset:8832
	global_load_dwordx4 v[98:101], v[126:127], off offset:-2000
	global_load_dwordx4 v[102:105], v[126:127], off offset:-2016
	global_load_dwordx4 v[106:109], v[126:127], off offset:-2032
	global_load_dwordx4 v[110:113], v[126:127], off offset:-2048
	global_load_dwordx4 v[114:117], v[126:127], off offset:48
	global_load_dwordx4 v[118:121], v[126:127], off offset:32
	global_load_dwordx4 v[122:125], v[126:127], off offset:16
	s_nop 0
	global_load_dwordx4 v[126:129], v[126:127], off
	s_waitcnt lgkmcnt(10)
	s_nop 0
	s_nop 0
	v_mfma_f32_16x16x32_bf16 v[130:133], v[204:207], v[6:9], 0
	ds_read_b128 v[204:207], v153 offset:8896
	v_mov_b32_e32 v150, v156
	s_add_u32 s44, s44, 0x80000
	s_waitcnt lgkmcnt(10)
	v_mfma_f32_16x16x32_bf16 v[130:133], v[208:211], v[2:5], v[130:133]
	ds_read_b128 v[208:211], v153 offset:8960
	s_nop 0
	s_addc_u32 s45, s45, 0
	s_waitcnt lgkmcnt(10)
	v_mfma_f32_16x16x32_bf16 v[130:133], v[212:215], v[10:13], v[130:133]
	ds_read_b128 v[212:215], v153 offset:9024
	s_nop 0
	s_cmp_eq_u32 s44, 0x180000
	s_waitcnt lgkmcnt(10)
	v_mfma_f32_16x16x32_bf16 v[130:133], v[216:219], v[14:17], v[130:133]
	ds_read_b128 v[216:219], v153 offset:9088
	s_waitcnt lgkmcnt(10)
	v_mfma_f32_16x16x32_bf16 v[130:133], v[220:223], v[18:21], v[130:133]
	ds_read_b128 v[220:223], v153 offset:9152
	s_waitcnt lgkmcnt(10)
	v_mfma_f32_16x16x32_bf16 v[130:133], v[224:227], v[22:25], v[130:133]
	ds_read_b128 v[224:227], v153 offset:17408
	s_waitcnt lgkmcnt(10)
	v_mfma_f32_16x16x32_bf16 v[130:133], v[228:231], v[26:29], v[130:133]
	ds_read_b128 v[228:231], v153 offset:17472
	s_waitcnt lgkmcnt(10)
	v_mfma_f32_16x16x32_bf16 v[130:133], v[232:235], v[30:33], v[130:133]
	ds_read_b128 v[232:235], v153 offset:17536
	s_nop 6
	v_mul_f32_e32 v156, 0x3fb8aa3b, v130
	s_waitcnt lgkmcnt(10)
	v_mfma_f32_16x16x32_bf16 v[134:137], v[236:239], v[6:9], 0
	ds_read_b128 v[236:239], v153 offset:17600
	v_mul_f32_e32 v159, 0x3fb8aa3b, v131
	v_max3_f32 v156, v156, s78, v159
	v_mul_f32_e32 v159, 0x3fb8aa3b, v132
	s_waitcnt lgkmcnt(10)
	v_mfma_f32_16x16x32_bf16 v[134:137], v[240:243], v[2:5], v[134:137]
	ds_read_b128 v[240:243], v153 offset:17664
	v_mul_f32_e32 v160, 0x3fb8aa3b, v133
	v_max3_f32 v156, v156, v159, v160
	s_waitcnt lgkmcnt(10)
	v_mfma_f32_16x16x32_bf16 v[134:137], v[244:247], v[10:13], v[134:137]
	ds_read_b128 v[244:247], v153 offset:17728
	s_waitcnt lgkmcnt(10)
	v_mfma_f32_16x16x32_bf16 v[134:137], v[204:207], v[14:17], v[134:137]
	ds_read_b128 v[204:207], v153 offset:17792
	s_waitcnt lgkmcnt(10)
	v_mfma_f32_16x16x32_bf16 v[134:137], v[208:211], v[18:21], v[134:137]
	ds_read_b128 v[208:211], v153 offset:17856
	s_waitcnt lgkmcnt(10)
	v_mfma_f32_16x16x32_bf16 v[134:137], v[212:215], v[22:25], v[134:137]
	ds_read_b128 v[212:215], v153 offset:26112
	s_waitcnt lgkmcnt(10)
	v_mfma_f32_16x16x32_bf16 v[134:137], v[216:219], v[26:29], v[134:137]
	ds_read_b128 v[216:219], v153 offset:26176
	s_waitcnt lgkmcnt(10)
	v_mfma_f32_16x16x32_bf16 v[134:137], v[220:223], v[30:33], v[134:137]
	ds_read_b128 v[220:223], v153 offset:26240
	s_nop 6
	v_mul_f32_e32 v159, 0x3fb8aa3b, v134
	s_waitcnt lgkmcnt(10)
	v_mfma_f32_16x16x32_bf16 v[138:141], v[224:227], v[6:9], 0
	ds_read_b128 v[224:227], v153 offset:26304
	v_mul_f32_e32 v160, 0x3fb8aa3b, v135
	v_max3_f32 v156, v156, v159, v160
	v_mul_f32_e32 v159, 0x3fb8aa3b, v136
	s_waitcnt lgkmcnt(10)
	v_mfma_f32_16x16x32_bf16 v[138:141], v[228:231], v[2:5], v[138:141]
	ds_read_b128 v[228:231], v153 offset:26368
	v_mul_f32_e32 v160, 0x3fb8aa3b, v137
	v_max3_f32 v156, v156, v159, v160
	s_waitcnt lgkmcnt(10)
	v_mfma_f32_16x16x32_bf16 v[138:141], v[232:235], v[10:13], v[138:141]
	ds_read_b128 v[232:235], v153 offset:26432
	s_waitcnt lgkmcnt(10)
	v_mfma_f32_16x16x32_bf16 v[138:141], v[236:239], v[14:17], v[138:141]
	ds_read_b128 v[236:239], v153 offset:26496
	s_waitcnt lgkmcnt(10)
	v_mfma_f32_16x16x32_bf16 v[138:141], v[240:243], v[18:21], v[138:141]
	ds_read_b128 v[240:243], v153 offset:26560
	s_waitcnt lgkmcnt(10)
	v_mfma_f32_16x16x32_bf16 v[138:141], v[244:247], v[22:25], v[138:141]
	ds_read_b64_tr_b16 v[244:245], v152 offset:34816
	ds_read_b64_tr_b16 v[246:247], v152 offset:43520
	s_waitcnt lgkmcnt(11)
	v_mfma_f32_16x16x32_bf16 v[138:141], v[204:207], v[26:29], v[138:141]
	ds_read_b64_tr_b16 v[204:205], v152 offset:34880
	ds_read_b64_tr_b16 v[206:207], v152 offset:43584
	s_waitcnt lgkmcnt(12)
	v_mfma_f32_16x16x32_bf16 v[138:141], v[208:211], v[30:33], v[138:141]
	s_nop 0
	s_nop 6
	v_mul_f32_e32 v159, 0x3fb8aa3b, v138
	s_waitcnt lgkmcnt(11)
; #define LAS __attribute__((address_space(3)))
; __device__ __forceinline__ void phase_xattn(CArgs& A, int l, unsigned char* lds, int tid) {
;     ...
;                 for (int ks = 0; ks < 8; ++ks) { const bf16x8 a = *(const bf16x8*)(Ks + (blk * 16 + r) * XA_KP + (32 * ks + 8 * g) * 2);
;                     sc[blk] = __builtin_amdgcn_mfma_f32_16x16x32_bf16(a, qf[ks], sc[blk], 0, 0, 0); } }
;             float mx = -INFINITY;
; #pragma unroll
;             for (int blk = 0; blk < 4; ++blk)
; #pragma unroll
;                 for (int e = 0; e < 4; ++e) { sc[blk][e] *= LOG2E; mx = fmaxf(mx, sc[blk][e]); }
;             mx = fmaxf(mx, __shfl_xor(mx, 16)); mx = fmaxf(mx, __shfl_xor(mx, 32));
;             const float mnew = fmaxf(m, mx); const float corr = __builtin_amdgcn_exp2f(m - mnew); m = mnew;
;             float ps = 0.f;
; #pragma unroll
;             for (int blk = 0; blk < 4; ++blk)
; #pragma unroll
;                 for (int e = 0; e < 4; ++e) { sc[blk][e] = __builtin_amdgcn_exp2f(sc[blk][e] - mnew); ps += sc[blk][e]; }
;             lsum = lsum * corr + ps;
; #pragma unroll
;             for (int i = 0; i < 16; ++i) o[i] *= corr;
; #pragma unroll
;             for (int m2 = 0; m2 < 2; ++m2) {
;                 const bf16x8 pb = pack_frag(sc[2 * m2][0], sc[2 * m2][1], sc[2 * m2][2], sc[2 * m2][3], sc[2 * m2 + 1][0], sc[2 * m2 + 1][1], sc[2 * m2 + 1][2], sc[2 * m2 + 1][3]);
; #pragma unroll
;                 for (int db = 0; db < 16; ++db) { const unsigned char* vp = Vt + (32 * m2 + 4 * g + (r >> 2)) * XA_VP + (16 * db + 4 * (r & 3)) * 2;
;                     const s16x4 lo = __builtin_amdgcn_ds_read_tr16_b64_v4i16((LAS s16x4*)vp), hi = __builtin_amdgcn_ds_read_tr16_b64_v4i16((LAS s16x4*)(vp + 16 * XA_VP));
;                     bf16x8 av; av[0] = lo[0]; av[1] = lo[1]; av[2] = lo[2]; av[3] = lo[3]; av[4] = hi[0]; av[5] = hi[1]; av[6] = hi[2]; av[7] = hi[3];
;                     o[db] = __builtin_amdgcn_mfma_f32_16x16x32_bf16(av, pb, o[db], 0, 0, 0); }
	v_mfma_f32_16x16x32_bf16 v[192:195], v[212:215], v[6:9], 0
	ds_read_b64_tr_b16 v[208:209], v152 offset:34912
	ds_read_b64_tr_b16 v[210:211], v152 offset:43616
	v_mul_f32_e32 v160, 0x3fb8aa3b, v139
	v_max3_f32 v156, v156, v159, v160
	v_mul_f32_e32 v159, 0x3fb8aa3b, v140
	s_waitcnt lgkmcnt(12)
	v_mfma_f32_16x16x32_bf16 v[192:195], v[216:219], v[2:5], v[192:195]
	s_nop 0
	v_mul_f32_e32 v160, 0x3fb8aa3b, v141
	v_max3_f32 v156, v156, v159, v160
	s_waitcnt lgkmcnt(11)
	v_mfma_f32_16x16x32_bf16 v[192:195], v[220:223], v[10:13], v[192:195]
	ds_read_b64_tr_b16 v[212:213], v152 offset:34944
	ds_read_b64_tr_b16 v[214:215], v152 offset:43648
	s_waitcnt lgkmcnt(12)
	v_mfma_f32_16x16x32_bf16 v[192:195], v[224:227], v[14:17], v[192:195]
	s_waitcnt lgkmcnt(11)
	s_nop 0
	v_mfma_f32_16x16x32_bf16 v[192:195], v[228:231], v[18:21], v[192:195]
	ds_read_b64_tr_b16 v[216:217], v152 offset:34976
	ds_read_b64_tr_b16 v[218:219], v152 offset:43680
	s_waitcnt lgkmcnt(12)
	v_mfma_f32_16x16x32_bf16 v[192:195], v[232:235], v[22:25], v[192:195]
	s_waitcnt lgkmcnt(11)
	s_nop 0
	v_mfma_f32_16x16x32_bf16 v[192:195], v[236:239], v[26:29], v[192:195]
	ds_read_b64_tr_b16 v[220:221], v152 offset:35008
	ds_read_b64_tr_b16 v[222:223], v152 offset:43712
	s_waitcnt lgkmcnt(12)
	v_mfma_f32_16x16x32_bf16 v[192:195], v[240:243], v[30:33], v[192:195]
	s_nop 7
	v_mul_f32_e32 v159, 0x3fb8aa3b, v192
	v_mul_f32_e32 v160, 0x3fb8aa3b, v193
	v_max3_f32 v156, v156, v159, v160
	v_mul_f32_e32 v159, 0x3fb8aa3b, v194
	v_mul_f32_e32 v160, 0x3fb8aa3b, v195
	v_max3_f32 v156, v156, v159, v160
	ds_bpermute_b32 v159, v151, v156
	s_waitcnt lgkmcnt(0)
	v_max_f32_e32 v159, v159, v159
	v_max_f32_e32 v156, v156, v159
	ds_bpermute_b32 v159, v147, v156
	s_waitcnt lgkmcnt(0)
	v_max3_f32 v156, v150, v156, v159
	v_fma_f32 v132, v132, s83, -v156
	v_exp_f32_e32 v160, v132
	v_fma_f32 v132, v133, s83, -v156
	v_fma_f32 v130, v130, s83, -v156
	v_exp_f32_e32 v133, v132
	v_fma_f32 v132, v134, s83, -v156
	v_exp_f32_e32 v159, v130
	v_fma_f32 v131, v131, s83, -v156
	v_exp_f32_e32 v134, v132
	v_fma_f32 v132, v135, s83, -v156
	v_exp_f32_e32 v131, v131
	v_exp_f32_e32 v135, v132
	v_fma_f32 v132, v136, s83, -v156
	v_exp_f32_e32 v136, v132
	v_fma_f32 v132, v137, s83, -v156
	v_exp_f32_e32 v137, v132
	v_fma_f32 v132, v138, s83, -v156
	v_add_f32_e32 v130, 0, v159
	v_exp_f32_e32 v161, v132
	v_fma_f32 v132, v139, s83, -v156
	v_add_f32_e32 v130, v131, v130
	v_exp_f32_e32 v196, v132
	v_fma_f32 v132, v140, s83, -v156
	v_add_f32_e32 v130, v160, v130
	v_exp_f32_e32 v140, v132
	v_fma_f32 v132, v141, s83, -v156
	v_add_f32_e32 v130, v133, v130
	v_exp_f32_e32 v141, v132
	v_fma_f32 v132, v192, s83, -v156
	v_add_f32_e32 v130, v134, v130
	v_exp_f32_e32 v197, v132
	v_fma_f32 v132, v193, s83, -v156
	v_sub_f32_e32 v150, v150, v156
	v_add_f32_e32 v130, v135, v130
	v_exp_f32_e32 v198, v132
	v_fma_f32 v132, v194, s83, -v156
	v_exp_f32_e32 v150, v150
	v_add_f32_e32 v130, v136, v130
	v_exp_f32_e32 v199, v132
	v_fma_f32 v132, v195, s83, -v156
	v_add_f32_e32 v130, v137, v130
	v_exp_f32_e32 v200, v132
	v_cvt_pk_bf16_f32 v132, v159, v131
	v_cvt_pk_bf16_f32 v133, v160, v133
	v_cvt_pk_bf16_f32 v134, v134, v135
	v_cvt_pk_bf16_f32 v135, v136, v137
	s_nop 0
	s_nop 0
	s_nop 0
	v_pk_mul_f32 v[88:89], v[88:89], v[150:151] op_sel_hi:[1,0]
	v_pk_mul_f32 v[86:87], v[86:87], v[150:151] op_sel_hi:[1,0]
	s_nop 0
	v_pk_mul_f32 v[64:65], v[64:65], v[150:151] op_sel_hi:[1,0]
	s_nop 0
	v_mfma_f32_16x16x32_bf16 v[86:89], v[244:247], v[132:135], v[86:89]
	ds_read_b64_tr_b16 v[224:225], v152 offset:35040
	ds_read_b64_tr_b16 v[226:227], v152 offset:43744
	ds_read_b64_tr_b16 v[228:229], v152 offset:35072
	ds_read_b64_tr_b16 v[230:231], v152 offset:43776
	ds_read_b64_tr_b16 v[232:233], v152 offset:35104
	ds_read_b64_tr_b16 v[234:235], v152 offset:43808
	ds_read_b64_tr_b16 v[236:237], v152 offset:35136
	ds_read_b64_tr_b16 v[238:239], v152 offset:43840
	ds_read_b64_tr_b16 v[240:241], v152 offset:35168
	ds_read_b64_tr_b16 v[242:243], v152 offset:43872
	ds_read_b64_tr_b16 v[244:245], v152 offset:35200
	ds_read_b64_tr_b16 v[246:247], v152 offset:43904
	v_pk_mul_f32 v[62:63], v[62:63], v[150:151] op_sel_hi:[1,0]
	v_pk_mul_f32 v[72:73], v[72:73], v[150:151] op_sel_hi:[1,0]
	v_pk_mul_f32 v[70:71], v[70:71], v[150:151] op_sel_hi:[1,0]
	s_nop 0
	v_mfma_f32_16x16x32_bf16 v[62:65], v[204:207], v[132:135], v[62:65]
	s_nop 0
	s_nop 0
	v_pk_mul_f32 v[80:81], v[80:81], v[150:151] op_sel_hi:[1,0]
	v_pk_mul_f32 v[78:79], v[78:79], v[150:151] op_sel_hi:[1,0]
	s_nop 0
	v_mfma_f32_16x16x32_bf16 v[70:73], v[208:211], v[132:135], v[70:73]
	s_nop 0
	s_nop 0
	v_pk_mul_f32 v[92:93], v[92:93], v[150:151] op_sel_hi:[1,0]
	v_pk_mul_f32 v[90:91], v[90:91], v[150:151] op_sel_hi:[1,0]
	s_nop 0
	v_mfma_f32_16x16x32_bf16 v[78:81], v[212:215], v[132:135], v[78:81]
	s_nop 0
	s_nop 0
	v_pk_mul_f32 v[84:85], v[84:85], v[150:151] op_sel_hi:[1,0]
	v_pk_mul_f32 v[82:83], v[82:83], v[150:151] op_sel_hi:[1,0]
	s_nop 0
	v_mfma_f32_16x16x32_bf16 v[90:93], v[216:219], v[132:135], v[90:93]
	s_nop 0
	s_nop 0
	v_pk_mul_f32 v[96:97], v[96:97], v[150:151] op_sel_hi:[1,0]
	v_pk_mul_f32 v[94:95], v[94:95], v[150:151] op_sel_hi:[1,0]
	s_nop 0
	v_mfma_f32_16x16x32_bf16 v[82:85], v[220:223], v[132:135], v[82:85]
	s_nop 0
	s_nop 0
	v_pk_mul_f32 v[76:77], v[76:77], v[150:151] op_sel_hi:[1,0]
	v_pk_mul_f32 v[74:75], v[74:75], v[150:151] op_sel_hi:[1,0]
	s_waitcnt lgkmcnt(10)
	v_mfma_f32_16x16x32_bf16 v[94:97], v[224:227], v[132:135], v[94:97]
	ds_read_b64_tr_b16 v[204:205], v152 offset:35232
	ds_read_b64_tr_b16 v[206:207], v152 offset:43936
	v_pk_mul_f32 v[60:61], v[60:61], v[150:151] op_sel_hi:[1,0]
	v_pk_mul_f32 v[58:59], v[58:59], v[150:151] op_sel_hi:[1,0]
	s_waitcnt lgkmcnt(10)
; #define LAS __attribute__((address_space(3)))
; __device__ __forceinline__ void phase_xattn(CArgs& A, int l, unsigned char* lds, int tid) {
;     ...
;             lsum = lsum * corr + ps;
; #pragma unroll
;             for (int i = 0; i < 16; ++i) o[i] *= corr;
; #pragma unroll
;             for (int m2 = 0; m2 < 2; ++m2) {
;                 const bf16x8 pb = pack_frag(sc[2 * m2][0], sc[2 * m2][1], sc[2 * m2][2], sc[2 * m2][3], sc[2 * m2 + 1][0], sc[2 * m2 + 1][1], sc[2 * m2 + 1][2], sc[2 * m2 + 1][3]);
; #pragma unroll
;                 for (int db = 0; db < 16; ++db) { const unsigned char* vp = Vt + (32 * m2 + 4 * g + (r >> 2)) * XA_VP + (16 * db + 4 * (r & 3)) * 2;
;                     const s16x4 lo = __builtin_amdgcn_ds_read_tr16_b64_v4i16((LAS s16x4*)vp), hi = __builtin_amdgcn_ds_read_tr16_b64_v4i16((LAS s16x4*)(vp + 16 * XA_VP));
;                     bf16x8 av; av[0] = lo[0]; av[1] = lo[1]; av[2] = lo[2]; av[3] = lo[3]; av[4] = hi[0]; av[5] = hi[1]; av[6] = hi[2]; av[7] = hi[3];
;                     o[db] = __builtin_amdgcn_mfma_f32_16x16x32_bf16(av, pb, o[db], 0, 0, 0); }
;             }
	v_mfma_f32_16x16x32_bf16 v[74:77], v[228:231], v[132:135], v[74:77]
	ds_read_b64_tr_b16 v[208:209], v152 offset:35264
	ds_read_b64_tr_b16 v[210:211], v152 offset:43968
	v_pk_mul_f32 v[56:57], v[56:57], v[150:151] op_sel_hi:[1,0]
	v_pk_mul_f32 v[54:55], v[54:55], v[150:151] op_sel_hi:[1,0]
	s_waitcnt lgkmcnt(10)
	v_mfma_f32_16x16x32_bf16 v[58:61], v[232:235], v[132:135], v[58:61]
	ds_read_b64_tr_b16 v[212:213], v152 offset:34848
	ds_read_b64_tr_b16 v[214:215], v152 offset:43552
	v_pk_mul_f32 v[52:53], v[52:53], v[150:151] op_sel_hi:[1,0]
	v_pk_mul_f32 v[50:51], v[50:51], v[150:151] op_sel_hi:[1,0]
	s_waitcnt lgkmcnt(10)
	v_mfma_f32_16x16x32_bf16 v[54:57], v[236:239], v[132:135], v[54:57]
	ds_read_b64_tr_b16 v[216:217], v152 offset:35296
	ds_read_b64_tr_b16 v[218:219], v152 offset:44000
	v_pk_mul_f32 v[48:49], v[48:49], v[150:151] op_sel_hi:[1,0]
	v_pk_mul_f32 v[46:47], v[46:47], v[150:151] op_sel_hi:[1,0]
	s_waitcnt lgkmcnt(10)
	v_mfma_f32_16x16x32_bf16 v[50:53], v[240:243], v[132:135], v[50:53]
	ds_read_b64_tr_b16 v[220:221], v152 offset:52224
	ds_read_b64_tr_b16 v[222:223], v152 offset:60928
	v_pk_mul_f32 v[44:45], v[44:45], v[150:151] op_sel_hi:[1,0]
	v_pk_mul_f32 v[42:43], v[42:43], v[150:151] op_sel_hi:[1,0]
	s_waitcnt lgkmcnt(10)
	v_mfma_f32_16x16x32_bf16 v[46:49], v[244:247], v[132:135], v[46:49]
	ds_read_b64_tr_b16 v[224:225], v152 offset:52288
	ds_read_b64_tr_b16 v[226:227], v152 offset:60992
	v_pk_mul_f32 v[40:41], v[40:41], v[150:151] op_sel_hi:[1,0]
	v_pk_mul_f32 v[38:39], v[38:39], v[150:151] op_sel_hi:[1,0]
	s_waitcnt lgkmcnt(10)
	v_mfma_f32_16x16x32_bf16 v[42:45], v[204:207], v[132:135], v[42:45]
	ds_read_b64_tr_b16 v[228:229], v152 offset:52320
	ds_read_b64_tr_b16 v[230:231], v152 offset:61024
	v_pk_mul_f32 v[68:69], v[68:69], v[150:151] op_sel_hi:[1,0]
	v_pk_mul_f32 v[66:67], v[66:67], v[150:151] op_sel_hi:[1,0]
	s_waitcnt lgkmcnt(10)
	v_mfma_f32_16x16x32_bf16 v[38:41], v[208:211], v[132:135], v[38:41]
	ds_read_b64_tr_b16 v[232:233], v152 offset:52352
	ds_read_b64_tr_b16 v[234:235], v152 offset:61056
	v_pk_mul_f32 v[36:37], v[36:37], v[150:151] op_sel_hi:[1,0]
	v_pk_mul_f32 v[34:35], v[34:35], v[150:151] op_sel_hi:[1,0]
	s_waitcnt lgkmcnt(10)
	v_mfma_f32_16x16x32_bf16 v[66:69], v[212:215], v[132:135], v[66:69]
	ds_read_b64_tr_b16 v[236:237], v152 offset:52384
	ds_read_b64_tr_b16 v[238:239], v152 offset:61088
	v_add_f32_e32 v130, v161, v130
	v_add_f32_e32 v130, v196, v130
	v_add_f32_e32 v130, v140, v130
	s_waitcnt lgkmcnt(10)
	v_mfma_f32_16x16x32_bf16 v[34:37], v[216:219], v[132:135], v[34:37]
	ds_read_b64_tr_b16 v[240:241], v152 offset:52416
	ds_read_b64_tr_b16 v[242:243], v152 offset:61120
	v_cvt_pk_bf16_f32 v132, v161, v196
	v_cvt_pk_bf16_f32 v133, v140, v141
	v_cvt_pk_bf16_f32 v134, v197, v198
	v_cvt_pk_bf16_f32 v135, v199, v200
	s_waitcnt lgkmcnt(10)
	s_nop 0
	s_nop 0
	s_nop 0
	v_mfma_f32_16x16x32_bf16 v[86:89], v[220:223], v[132:135], v[86:89]
	ds_read_b64_tr_b16 v[244:245], v152 offset:52448
	ds_read_b64_tr_b16 v[246:247], v152 offset:61152
	s_nop 0
	v_add_f32_e32 v130, v141, v130
	s_waitcnt lgkmcnt(10)
	v_mfma_f32_16x16x32_bf16 v[62:65], v[224:227], v[132:135], v[62:65]
	ds_read_b64_tr_b16 v[204:205], v152 offset:52480
	ds_read_b64_tr_b16 v[206:207], v152 offset:61184
	v_add_f32_e32 v130, v197, v130
	v_add_f32_e32 v130, v198, v130
	s_waitcnt lgkmcnt(10)
	v_mfma_f32_16x16x32_bf16 v[70:73], v[228:231], v[132:135], v[70:73]
	ds_read_b64_tr_b16 v[208:209], v152 offset:52512
	ds_read_b64_tr_b16 v[210:211], v152 offset:61216
	v_add_f32_e32 v130, v199, v130
	v_add_f32_e32 v130, v200, v130
	s_waitcnt lgkmcnt(10)
	v_mfma_f32_16x16x32_bf16 v[78:81], v[232:235], v[132:135], v[78:81]
	ds_read_b64_tr_b16 v[212:213], v152 offset:52544
	ds_read_b64_tr_b16 v[214:215], v152 offset:61248
	v_fmac_f32_e32 v130, v158, v150
	s_waitcnt lgkmcnt(10)
	v_mfma_f32_16x16x32_bf16 v[90:93], v[236:239], v[132:135], v[90:93]
	ds_read_b64_tr_b16 v[216:217], v152 offset:52576
	ds_read_b64_tr_b16 v[218:219], v152 offset:61280
	s_waitcnt lgkmcnt(10)
	v_mfma_f32_16x16x32_bf16 v[82:85], v[240:243], v[132:135], v[82:85]
	ds_read_b64_tr_b16 v[220:221], v152 offset:52608
	ds_read_b64_tr_b16 v[222:223], v152 offset:61312
	s_waitcnt lgkmcnt(10)
	v_mfma_f32_16x16x32_bf16 v[94:97], v[244:247], v[132:135], v[94:97]
	ds_read_b64_tr_b16 v[224:225], v152 offset:52640
	ds_read_b64_tr_b16 v[226:227], v152 offset:61344
	s_waitcnt lgkmcnt(10)
	v_mfma_f32_16x16x32_bf16 v[74:77], v[204:207], v[132:135], v[74:77]
	ds_read_b64_tr_b16 v[228:229], v152 offset:52672
	ds_read_b64_tr_b16 v[230:231], v152 offset:61376
	s_waitcnt lgkmcnt(10)
	v_mfma_f32_16x16x32_bf16 v[58:61], v[208:211], v[132:135], v[58:61]
	ds_read_b64_tr_b16 v[232:233], v152 offset:52256
	ds_read_b64_tr_b16 v[234:235], v152 offset:60960
	s_waitcnt lgkmcnt(10)
	v_mfma_f32_16x16x32_bf16 v[54:57], v[212:215], v[132:135], v[54:57]
	ds_read_b64_tr_b16 v[236:237], v152 offset:52704
	ds_read_b64_tr_b16 v[238:239], v152 offset:61408
	s_waitcnt lgkmcnt(10)
	v_mfma_f32_16x16x32_bf16 v[50:53], v[216:219], v[132:135], v[50:53]
	s_waitcnt lgkmcnt(8)
	s_nop 0
	s_nop 0
	v_mfma_f32_16x16x32_bf16 v[46:49], v[220:223], v[132:135], v[46:49]
	s_waitcnt lgkmcnt(6)
	s_nop 0
	s_nop 0
	v_mfma_f32_16x16x32_bf16 v[42:45], v[224:227], v[132:135], v[42:45]
	s_waitcnt lgkmcnt(4)
	s_nop 0
	s_nop 0
	v_mfma_f32_16x16x32_bf16 v[38:41], v[228:231], v[132:135], v[38:41]
	s_waitcnt lgkmcnt(2)
	s_nop 0
	v_mfma_f32_16x16x32_bf16 v[66:69], v[232:235], v[132:135], v[66:69]
	s_waitcnt lgkmcnt(0)
	v_mfma_f32_16x16x32_bf16 v[34:37], v[236:239], v[132:135], v[34:37]
	s_cbranch_scc0 .LBB0_145
	s_barrier
; __device__ __forceinline__ void phase_xattn(CArgs& A, int l, unsigned char* lds, int tid) {
;     ...
;         for (int kt = 0; kt < 4; ++kt) {
;             __syncthreads();
; #pragma unroll
;             for (int i = 0; i < 4; ++i) *(u32x4*)(Ks + skey * XA_KP + (sdc + i * 8) * 2) = kr[i];
; #pragma unroll
;             for (int i = 0; i < 4; ++i) *(u32x4*)(Vt + skey * XA_VP + (sdc + i * 8) * 2) = vr[i];
;             __syncthreads();
;             if (kt + 1 < 4) {
; #pragma unroll
;                 for (int i = 0; i < 4; ++i) { kr[i] = *(const u32x4*)(kvbase + (size_t)(kt + 1) * 64 * 4096 + i * 8); vr[i] = *(const u32x4*)(kvbase + (size_t)(kt + 1) * 64 * 4096 + 1024 + i * 8); } }
;             f32x4 sc[4];
; #pragma unroll
;             for (int blk = 0; blk < 4; ++blk) { sc[blk] = (f32x4){0.f, 0.f, 0.f, 0.f};
; #pragma unroll
;                 for (int ks = 0; ks < 8; ++ks) { const bf16x8 a = *(const bf16x8*)(Ks + (blk * 16 + r) * XA_KP + (32 * ks + 8 * g) * 2);
;                     sc[blk] = __builtin_amdgcn_mfma_f32_16x16x32_bf16(a, qf[ks], sc[blk], 0, 0, 0); } }
	s_waitcnt vmcnt(4)
	ds_write_b128 v157, v[110:113]
	ds_write_b128 v157, v[106:109] offset:16
	ds_write_b128 v157, v[102:105] offset:32
	ds_write_b128 v157, v[98:101] offset:48
	s_waitcnt vmcnt(0)
	ds_write_b128 v155, v[126:129] offset:34816
	ds_write_b128 v155, v[122:125] offset:34832
	ds_write_b128 v155, v[118:121] offset:34848
	ds_write_b128 v155, v[114:117] offset:34864
	s_waitcnt lgkmcnt(0)
	s_barrier
	ds_read_b128 v[204:207], v153
	ds_read_b128 v[208:211], v153 offset:64
	ds_read_b128 v[212:215], v153 offset:128
	ds_read_b128 v[216:219], v153 offset:192
	ds_read_b128 v[220:223], v153 offset:256
	ds_read_b128 v[224:227], v153 offset:320
	ds_read_b128 v[228:231], v153 offset:384
	ds_read_b128 v[232:235], v153 offset:448
	ds_read_b128 v[236:239], v153 offset:8704
	ds_read_b128 v[240:243], v153 offset:8768
	ds_read_b128 v[244:247], v153 offset:8832
	s_waitcnt lgkmcnt(10)
	v_mfma_f32_16x16x32_bf16 v[98:101], v[204:207], v[6:9], 0
	ds_read_b128 v[204:207], v153 offset:8896
	s_lshl_b32 s14, s36, 1
	s_waitcnt lgkmcnt(10)
	s_nop 0
	v_mfma_f32_16x16x32_bf16 v[98:101], v[208:211], v[2:5], v[98:101]
	ds_read_b128 v[208:211], v153 offset:8960
	s_waitcnt lgkmcnt(10)
	v_mfma_f32_16x16x32_bf16 v[98:101], v[212:215], v[10:13], v[98:101]
	ds_read_b128 v[212:215], v153 offset:9024
	s_waitcnt lgkmcnt(10)
	v_mfma_f32_16x16x32_bf16 v[98:101], v[216:219], v[14:17], v[98:101]
	ds_read_b128 v[216:219], v153 offset:9088
	s_waitcnt lgkmcnt(10)
	v_mfma_f32_16x16x32_bf16 v[98:101], v[220:223], v[18:21], v[98:101]
	ds_read_b128 v[220:223], v153 offset:9152
	s_waitcnt lgkmcnt(10)
	v_mfma_f32_16x16x32_bf16 v[98:101], v[224:227], v[22:25], v[98:101]
	ds_read_b128 v[224:227], v153 offset:17408
	s_waitcnt lgkmcnt(10)
	v_mfma_f32_16x16x32_bf16 v[98:101], v[228:231], v[26:29], v[98:101]
	ds_read_b128 v[228:231], v153 offset:17472
	s_waitcnt lgkmcnt(10)
	v_mfma_f32_16x16x32_bf16 v[98:101], v[232:235], v[30:33], v[98:101]
	ds_read_b128 v[232:235], v153 offset:17536
	s_waitcnt lgkmcnt(10)
	v_mfma_f32_16x16x32_bf16 v[102:105], v[236:239], v[6:9], 0
	ds_read_b128 v[236:239], v153 offset:17600
	s_waitcnt lgkmcnt(10)
	v_mfma_f32_16x16x32_bf16 v[102:105], v[240:243], v[2:5], v[102:105]
	ds_read_b128 v[240:243], v153 offset:17664
	s_waitcnt lgkmcnt(10)
	v_mfma_f32_16x16x32_bf16 v[102:105], v[244:247], v[10:13], v[102:105]
	ds_read_b128 v[244:247], v153 offset:17728
	s_waitcnt lgkmcnt(10)
	v_mfma_f32_16x16x32_bf16 v[102:105], v[204:207], v[14:17], v[102:105]
	ds_read_b128 v[204:207], v153 offset:17792
	s_waitcnt lgkmcnt(10)
	v_mfma_f32_16x16x32_bf16 v[102:105], v[208:211], v[18:21], v[102:105]
	ds_read_b128 v[208:211], v153 offset:17856
	s_waitcnt lgkmcnt(10)
	v_mfma_f32_16x16x32_bf16 v[102:105], v[212:215], v[22:25], v[102:105]
	ds_read_b128 v[212:215], v153 offset:26112
	s_waitcnt lgkmcnt(10)
	v_mfma_f32_16x16x32_bf16 v[102:105], v[216:219], v[26:29], v[102:105]
	ds_read_b128 v[216:219], v153 offset:26176
	s_waitcnt lgkmcnt(10)
	v_mfma_f32_16x16x32_bf16 v[102:105], v[220:223], v[30:33], v[102:105]
	ds_read_b128 v[220:223], v153 offset:26240
	s_waitcnt lgkmcnt(10)
	v_mfma_f32_16x16x32_bf16 v[106:109], v[224:227], v[6:9], 0
	ds_read_b128 v[224:227], v153 offset:26304
	s_waitcnt lgkmcnt(10)
	v_mfma_f32_16x16x32_bf16 v[106:109], v[228:231], v[2:5], v[106:109]
	ds_read_b128 v[228:231], v153 offset:26368
	s_waitcnt lgkmcnt(10)
	v_mfma_f32_16x16x32_bf16 v[106:109], v[232:235], v[10:13], v[106:109]
	ds_read_b128 v[232:235], v153 offset:26432
	s_waitcnt lgkmcnt(10)
	v_mfma_f32_16x16x32_bf16 v[106:109], v[236:239], v[14:17], v[106:109]
	ds_read_b128 v[236:239], v153 offset:26496
	s_waitcnt lgkmcnt(10)
	v_mfma_f32_16x16x32_bf16 v[106:109], v[240:243], v[18:21], v[106:109]
	ds_read_b128 v[240:243], v153 offset:26560
	s_waitcnt lgkmcnt(10)
	v_mfma_f32_16x16x32_bf16 v[106:109], v[244:247], v[22:25], v[106:109]
	ds_read_b64_tr_b16 v[244:245], v152 offset:35008
	ds_read_b64_tr_b16 v[246:247], v152 offset:43712
	s_waitcnt lgkmcnt(11)
	v_mfma_f32_16x16x32_bf16 v[106:109], v[204:207], v[26:29], v[106:109]
	ds_read_b64_tr_b16 v[204:205], v152 offset:35040
	ds_read_b64_tr_b16 v[206:207], v152 offset:43744
	s_waitcnt lgkmcnt(12)
	v_mfma_f32_16x16x32_bf16 v[106:109], v[208:211], v[30:33], v[106:109]
	s_waitcnt lgkmcnt(11)
	s_nop 0
	v_mfma_f32_16x16x32_bf16 v[6:9], v[212:215], v[6:9], 0
	ds_read_b64_tr_b16 v[208:209], v152 offset:35072
	ds_read_b64_tr_b16 v[210:211], v152 offset:43776
	s_waitcnt lgkmcnt(12)
	v_mfma_f32_16x16x32_bf16 v[2:5], v[216:219], v[2:5], v[6:9]
	s_nop 4
	s_waitcnt lgkmcnt(11)
	s_nop 0
	v_mfma_f32_16x16x32_bf16 v[2:5], v[220:223], v[10:13], v[2:5]
	ds_read_b64_tr_b16 v[212:213], v152 offset:35104
	ds_read_b64_tr_b16 v[214:215], v152 offset:43808
	s_waitcnt lgkmcnt(12)
	v_mfma_f32_16x16x32_bf16 v[2:5], v[224:227], v[14:17], v[2:5]
	s_waitcnt lgkmcnt(11)
	s_nop 0
	v_mfma_f32_16x16x32_bf16 v[2:5], v[228:231], v[18:21], v[2:5]
	ds_read_b64_tr_b16 v[216:217], v152 offset:35136
	ds_read_b64_tr_b16 v[218:219], v152 offset:43840
	s_waitcnt lgkmcnt(12)
	v_mfma_f32_16x16x32_bf16 v[2:5], v[232:235], v[22:25], v[2:5]
	s_waitcnt lgkmcnt(11)
	s_nop 0
	v_mfma_f32_16x16x32_bf16 v[2:5], v[236:239], v[26:29], v[2:5]
	ds_read_b64_tr_b16 v[220:221], v152 offset:35168
	ds_read_b64_tr_b16 v[222:223], v152 offset:43872
	s_waitcnt lgkmcnt(12)
; #define LAS __attribute__((address_space(3)))
; __device__ __forceinline__ void phase_xattn(CArgs& A, int l, unsigned char* lds, int tid) {
;     ...
;             float mx = -INFINITY;
; #pragma unroll
;             for (int blk = 0; blk < 4; ++blk)
; #pragma unroll
;                 for (int e = 0; e < 4; ++e) { sc[blk][e] *= LOG2E; mx = fmaxf(mx, sc[blk][e]); }
;             mx = fmaxf(mx, __shfl_xor(mx, 16)); mx = fmaxf(mx, __shfl_xor(mx, 32));
;             const float mnew = fmaxf(m, mx); const float corr = __builtin_amdgcn_exp2f(m - mnew); m = mnew;
;             float ps = 0.f;
; #pragma unroll
;             for (int blk = 0; blk < 4; ++blk)
; #pragma unroll
;                 for (int e = 0; e < 4; ++e) { sc[blk][e] = __builtin_amdgcn_exp2f(sc[blk][e] - mnew); ps += sc[blk][e]; }
;             lsum = lsum * corr + ps;
; #pragma unroll
;             for (int i = 0; i < 16; ++i) o[i] *= corr;
; #pragma unroll
;             for (int m2 = 0; m2 < 2; ++m2) {
;                 const bf16x8 pb = pack_frag(sc[2 * m2][0], sc[2 * m2][1], sc[2 * m2][2], sc[2 * m2][3], sc[2 * m2 + 1][0], sc[2 * m2 + 1][1], sc[2 * m2 + 1][2], sc[2 * m2 + 1][3]);
; #pragma unroll
;                 for (int db = 0; db < 16; ++db) { const unsigned char* vp = Vt + (32 * m2 + 4 * g + (r >> 2)) * XA_VP + (16 * db + 4 * (r & 3)) * 2;
;                     const s16x4 lo = __builtin_amdgcn_ds_read_tr16_b64_v4i16((LAS s16x4*)vp), hi = __builtin_amdgcn_ds_read_tr16_b64_v4i16((LAS s16x4*)(vp + 16 * XA_VP));
;                     bf16x8 av; av[0] = lo[0]; av[1] = lo[1]; av[2] = lo[2]; av[3] = lo[3]; av[4] = hi[0]; av[5] = hi[1]; av[6] = hi[2]; av[7] = hi[3];
;                     o[db] = __builtin_amdgcn_mfma_f32_16x16x32_bf16(av, pb, o[db], 0, 0, 0); }
	v_mfma_f32_16x16x32_bf16 v[2:5], v[240:243], v[30:33], v[2:5]
	v_mul_f32_e32 v6, 0x3fb8aa3b, v98
	v_mul_f32_e32 v7, 0x3fb8aa3b, v99
	v_max3_f32 v6, v6, s78, v7
	v_mul_f32_e32 v7, 0x3fb8aa3b, v100
	v_mul_f32_e32 v8, 0x3fb8aa3b, v101
	v_max3_f32 v6, v6, v7, v8
	v_mul_f32_e32 v7, 0x3fb8aa3b, v102
	v_mul_f32_e32 v8, 0x3fb8aa3b, v103
	v_max3_f32 v6, v6, v7, v8
	v_mul_f32_e32 v7, 0x3fb8aa3b, v104
	v_mul_f32_e32 v8, 0x3fb8aa3b, v105
	v_max3_f32 v6, v6, v7, v8
	v_mul_f32_e32 v7, 0x3fb8aa3b, v106
	v_mul_f32_e32 v8, 0x3fb8aa3b, v107
	v_max3_f32 v6, v6, v7, v8
	v_mul_f32_e32 v7, 0x3fb8aa3b, v108
	v_mul_f32_e32 v8, 0x3fb8aa3b, v109
	v_max3_f32 v6, v6, v7, v8
	v_mul_f32_e32 v7, 0x3fb8aa3b, v2
	v_mul_f32_e32 v8, 0x3fb8aa3b, v3
	v_max3_f32 v6, v6, v7, v8
	v_mul_f32_e32 v7, 0x3fb8aa3b, v4
	v_mul_f32_e32 v8, 0x3fb8aa3b, v5
	v_max3_f32 v6, v6, v7, v8
	ds_bpermute_b32 v7, v151, v6
	s_waitcnt lgkmcnt(0)
	v_max_f32_e32 v7, v7, v7
	v_max_f32_e32 v6, v6, v7
	ds_bpermute_b32 v7, v147, v6
	s_waitcnt lgkmcnt(0)
	v_max3_f32 v6, v156, v6, v7
	v_sub_f32_e32 v7, v156, v6
	v_exp_f32_e32 v110, v7
	v_fma_f32 v7, v98, s83, -v6
	v_exp_f32_e32 v119, v7
	v_fma_f32 v8, v99, s83, -v6
	v_exp_f32_e32 v120, v8
	v_fma_f32 v8, v100, s83, -v6
	v_exp_f32_e32 v121, v8
	v_fma_f32 v8, v101, s83, -v6
	v_exp_f32_e32 v122, v8
	v_fma_f32 v8, v102, s83, -v6
	v_add_f32_e32 v7, 0, v119
	v_exp_f32_e32 v123, v8
	v_fma_f32 v8, v103, s83, -v6
	v_add_f32_e32 v7, v120, v7
	v_exp_f32_e32 v124, v8
	v_fma_f32 v8, v104, s83, -v6
	v_add_f32_e32 v7, v121, v7
	v_exp_f32_e32 v125, v8
	v_fma_f32 v8, v105, s83, -v6
	v_add_f32_e32 v7, v122, v7
	v_exp_f32_e32 v126, v8
	v_fma_f32 v8, v106, s83, -v6
	v_add_f32_e32 v7, v123, v7
	v_exp_f32_e32 v111, v8
	v_fma_f32 v8, v107, s83, -v6
	v_add_f32_e32 v7, v124, v7
	v_exp_f32_e32 v112, v8
	v_fma_f32 v8, v108, s83, -v6
	v_add_f32_e32 v7, v125, v7
	v_exp_f32_e32 v113, v8
	v_fma_f32 v8, v109, s83, -v6
	v_add_f32_e32 v7, v126, v7
	v_exp_f32_e32 v114, v8
	v_fma_f32 v2, v2, s83, -v6
	v_add_f32_e32 v7, v111, v7
	v_exp_f32_e32 v115, v2
	v_fma_f32 v2, v3, s83, -v6
	v_add_f32_e32 v7, v112, v7
	v_exp_f32_e32 v116, v2
	v_fma_f32 v2, v4, s83, -v6
	v_add_f32_e32 v7, v113, v7
	v_exp_f32_e32 v117, v2
	v_fma_f32 v2, v5, s83, -v6
	v_add_f32_e32 v127, v114, v7
	v_exp_f32_e32 v118, v2
	v_pk_mul_f32 v[2:3], v[34:35], v[110:111] op_sel_hi:[1,0]
	v_add_f32_e32 v34, v115, v127
	v_add_f32_e32 v34, v116, v34
	v_add_f32_e32 v34, v117, v34
	v_pk_mul_f32 v[102:103], v[66:67], v[110:111] op_sel_hi:[1,0]
	v_pk_mul_f32 v[66:67], v[82:83], v[110:111] op_sel_hi:[1,0]
	v_pk_mul_f32 v[32:33], v[76:77], v[110:111] op_sel_hi:[1,0]
	v_pk_mul_f32 v[30:31], v[74:75], v[110:111] op_sel_hi:[1,0]
	v_pk_mul_f32 v[28:29], v[60:61], v[110:111] op_sel_hi:[1,0]
	v_pk_mul_f32 v[26:27], v[58:59], v[110:111] op_sel_hi:[1,0]
	v_pk_mul_f32 v[24:25], v[56:57], v[110:111] op_sel_hi:[1,0]
	v_pk_mul_f32 v[22:23], v[54:55], v[110:111] op_sel_hi:[1,0]
	v_pk_mul_f32 v[20:21], v[52:53], v[110:111] op_sel_hi:[1,0]
	v_pk_mul_f32 v[18:19], v[50:51], v[110:111] op_sel_hi:[1,0]
	v_pk_mul_f32 v[16:17], v[48:49], v[110:111] op_sel_hi:[1,0]
	v_pk_mul_f32 v[14:15], v[46:47], v[110:111] op_sel_hi:[1,0]
	v_pk_mul_f32 v[12:13], v[44:45], v[110:111] op_sel_hi:[1,0]
	v_pk_mul_f32 v[10:11], v[42:43], v[110:111] op_sel_hi:[1,0]
	v_pk_mul_f32 v[8:9], v[40:41], v[110:111] op_sel_hi:[1,0]
	v_pk_mul_f32 v[6:7], v[38:39], v[110:111] op_sel_hi:[1,0]
	v_pk_mul_f32 v[4:5], v[36:37], v[110:111] op_sel_hi:[1,0]
	v_add_f32_e32 v82, v118, v34
	v_cvt_pk_bf16_f32 v74, v119, v120
	v_cvt_pk_bf16_f32 v75, v121, v122
	v_cvt_pk_bf16_f32 v76, v123, v124
	v_cvt_pk_bf16_f32 v77, v125, v126
	s_nop 0
	s_nop 0
	s_nop 0
	s_nop 0
	s_nop 0
	s_nop 0
	s_nop 0
	s_nop 0
	s_nop 0
	s_nop 0
	s_nop 0
	s_nop 0
	s_nop 0
	s_nop 0
	v_pk_mul_f32 v[104:105], v[68:69], v[110:111] op_sel_hi:[1,0]
	v_pk_mul_f32 v[68:69], v[84:85], v[110:111] op_sel_hi:[1,0]
	v_pk_mul_f32 v[100:101], v[64:65], v[110:111] op_sel_hi:[1,0]
	v_pk_mul_f32 v[98:99], v[62:63], v[110:111] op_sel_hi:[1,0]
	s_nop 0
	v_mfma_f32_16x16x32_bf16 v[58:61], v[244:247], v[74:77], v[66:69]
	ds_read_b64_tr_b16 v[224:225], v152 offset:35200
	ds_read_b64_tr_b16 v[226:227], v152 offset:43904
	ds_read_b64_tr_b16 v[228:229], v152 offset:35232
	ds_read_b64_tr_b16 v[230:231], v152 offset:43936
	ds_read_b64_tr_b16 v[232:233], v152 offset:35264
	ds_read_b64_tr_b16 v[234:235], v152 offset:43968
	ds_read_b64_tr_b16 v[236:237], v152 offset:34816
	ds_read_b64_tr_b16 v[238:239], v152 offset:43520
	ds_read_b64_tr_b16 v[240:241], v152 offset:34848
	ds_read_b64_tr_b16 v[242:243], v152 offset:43552
	ds_read_b64_tr_b16 v[244:245], v152 offset:34880
	ds_read_b64_tr_b16 v[246:247], v152 offset:43584
	s_nop 2
	s_nop 0
	s_nop 0
	v_pk_mul_f32 v[64:65], v[96:97], v[110:111] op_sel_hi:[1,0]
	v_pk_mul_f32 v[62:63], v[94:95], v[110:111] op_sel_hi:[1,0]
	v_pk_mul_f32 v[108:109], v[88:89], v[110:111] op_sel_hi:[1,0]
	v_pk_mul_f32 v[106:107], v[86:87], v[110:111] op_sel_hi:[1,0]
	s_nop 0
	v_mfma_f32_16x16x32_bf16 v[62:65], v[204:207], v[74:77], v[62:65]
	s_nop 0
	s_nop 0
	v_pk_mul_f32 v[88:89], v[72:73], v[110:111] op_sel_hi:[1,0]
	v_pk_mul_f32 v[86:87], v[70:71], v[110:111] op_sel_hi:[1,0]
	s_nop 0
	v_mfma_f32_16x16x32_bf16 v[30:33], v[208:211], v[74:77], v[30:33]
	s_nop 0
	s_nop 0
	v_pk_mul_f32 v[80:81], v[80:81], v[110:111] op_sel_hi:[1,0]
	v_pk_mul_f32 v[78:79], v[78:79], v[110:111] op_sel_hi:[1,0]
	s_nop 0
	v_mfma_f32_16x16x32_bf16 v[26:29], v[212:215], v[74:77], v[26:29]
	s_nop 0
	s_nop 0
	v_pk_mul_f32 v[72:73], v[92:93], v[110:111] op_sel_hi:[1,0]
	v_pk_mul_f32 v[70:71], v[90:91], v[110:111] op_sel_hi:[1,0]
	s_nop 0
	v_mfma_f32_16x16x32_bf16 v[22:25], v[216:219], v[74:77], v[22:25]
	s_nop 0
	s_nop 0
	v_fmac_f32_e32 v82, v130, v110
	s_nop 0
	v_mfma_f32_16x16x32_bf16 v[18:21], v[220:223], v[74:77], v[18:21]
	s_waitcnt lgkmcnt(10)
; #define LAS __attribute__((address_space(3)))
; __device__ __forceinline__ void phase_xattn(CArgs& A, int l, unsigned char* lds, int tid) {
;     ...
;             for (int m2 = 0; m2 < 2; ++m2) {
;                 const bf16x8 pb = pack_frag(sc[2 * m2][0], sc[2 * m2][1], sc[2 * m2][2], sc[2 * m2][3], sc[2 * m2 + 1][0], sc[2 * m2 + 1][1], sc[2 * m2 + 1][2], sc[2 * m2 + 1][3]);
; #pragma unroll
;                 for (int db = 0; db < 16; ++db) { const unsigned char* vp = Vt + (32 * m2 + 4 * g + (r >> 2)) * XA_VP + (16 * db + 4 * (r & 3)) * 2;
;                     const s16x4 lo = __builtin_amdgcn_ds_read_tr16_b64_v4i16((LAS s16x4*)vp), hi = __builtin_amdgcn_ds_read_tr16_b64_v4i16((LAS s16x4*)(vp + 16 * XA_VP));
;                     bf16x8 av; av[0] = lo[0]; av[1] = lo[1]; av[2] = lo[2]; av[3] = lo[3]; av[4] = hi[0]; av[5] = hi[1]; av[6] = hi[2]; av[7] = hi[3];
;                     o[db] = __builtin_amdgcn_mfma_f32_16x16x32_bf16(av, pb, o[db], 0, 0, 0); }
;             }
;         }
;         float ltot = lsum + __shfl_xor(lsum, 16); ltot += __shfl_xor(ltot, 32);
	s_nop 0
	s_nop 0
	v_mfma_f32_16x16x32_bf16 v[14:17], v[224:227], v[74:77], v[14:17]
	ds_read_b64_tr_b16 v[204:205], v152 offset:34912
	ds_read_b64_tr_b16 v[206:207], v152 offset:43616
	s_waitcnt lgkmcnt(10)
	v_mfma_f32_16x16x32_bf16 v[10:13], v[228:231], v[74:77], v[10:13]
	ds_read_b64_tr_b16 v[208:209], v152 offset:34944
	ds_read_b64_tr_b16 v[210:211], v152 offset:43648
	s_waitcnt lgkmcnt(10)
	v_mfma_f32_16x16x32_bf16 v[66:69], v[232:235], v[74:77], v[6:9]
	ds_read_b64_tr_b16 v[212:213], v152 offset:34976
	ds_read_b64_tr_b16 v[214:215], v152 offset:43680
	s_nop 2
	s_waitcnt lgkmcnt(10)
	s_nop 0
	v_mfma_f32_16x16x32_bf16 v[34:37], v[236:239], v[74:77], v[106:109]
	ds_read_b64_tr_b16 v[216:217], v152 offset:35296
	ds_read_b64_tr_b16 v[218:219], v152 offset:44000
	s_waitcnt lgkmcnt(10)
	v_mfma_f32_16x16x32_bf16 v[38:41], v[240:243], v[74:77], v[102:105]
	ds_read_b64_tr_b16 v[220:221], v152 offset:52224
	ds_read_b64_tr_b16 v[222:223], v152 offset:60928
	s_waitcnt lgkmcnt(10)
	v_mfma_f32_16x16x32_bf16 v[42:45], v[244:247], v[74:77], v[98:101]
	ds_read_b64_tr_b16 v[224:225], v152 offset:52256
	ds_read_b64_tr_b16 v[226:227], v152 offset:60960
	s_waitcnt lgkmcnt(10)
	v_mfma_f32_16x16x32_bf16 v[46:49], v[204:207], v[74:77], v[86:89]
	ds_read_b64_tr_b16 v[228:229], v152 offset:52288
	ds_read_b64_tr_b16 v[230:231], v152 offset:60992
	s_waitcnt lgkmcnt(10)
	v_mfma_f32_16x16x32_bf16 v[50:53], v[208:211], v[74:77], v[78:81]
	ds_read_b64_tr_b16 v[232:233], v152 offset:52320
	ds_read_b64_tr_b16 v[234:235], v152 offset:61024
	s_waitcnt lgkmcnt(10)
	v_mfma_f32_16x16x32_bf16 v[54:57], v[212:215], v[74:77], v[70:73]
	ds_read_b64_tr_b16 v[236:237], v152 offset:52352
	ds_read_b64_tr_b16 v[238:239], v152 offset:61056
	s_waitcnt lgkmcnt(10)
	v_mfma_f32_16x16x32_bf16 v[70:73], v[216:219], v[74:77], v[2:5]
	ds_read_b64_tr_b16 v[240:241], v152 offset:52384
	ds_read_b64_tr_b16 v[242:243], v152 offset:61088
	v_cvt_pk_bf16_f32 v74, v111, v112
	v_cvt_pk_bf16_f32 v75, v113, v114
	v_cvt_pk_bf16_f32 v76, v115, v116
	v_cvt_pk_bf16_f32 v77, v117, v118
	s_nop 2
	s_waitcnt lgkmcnt(10)
	s_nop 0
	s_nop 0
	s_nop 0
	s_nop 0
	v_mfma_f32_16x16x32_bf16 v[2:5], v[220:223], v[74:77], v[34:37]
	ds_read_b64_tr_b16 v[244:245], v152 offset:52416
	ds_read_b64_tr_b16 v[246:247], v152 offset:61120
	s_nop 2
	s_waitcnt lgkmcnt(10)
	s_nop 0
	s_nop 0
	v_mfma_f32_16x16x32_bf16 v[6:9], v[224:227], v[74:77], v[38:41]
	ds_read_b64_tr_b16 v[204:205], v152 offset:52480
	ds_read_b64_tr_b16 v[206:207], v152 offset:61184
	s_nop 2
	s_waitcnt lgkmcnt(10)
	s_nop 0
	s_nop 0
	v_mfma_f32_16x16x32_bf16 v[34:37], v[228:231], v[74:77], v[42:45]
	ds_read_b64_tr_b16 v[208:209], v152 offset:52512
	ds_read_b64_tr_b16 v[210:211], v152 offset:61216
	s_nop 2
	s_waitcnt lgkmcnt(10)
	s_nop 0
	s_nop 0
	v_mfma_f32_16x16x32_bf16 v[38:41], v[232:235], v[74:77], v[46:49]
	ds_read_b64_tr_b16 v[212:213], v152 offset:52544
	ds_read_b64_tr_b16 v[214:215], v152 offset:61248
	s_nop 2
	s_waitcnt lgkmcnt(10)
	s_nop 0
	s_nop 0
	v_mfma_f32_16x16x32_bf16 v[42:45], v[236:239], v[74:77], v[50:53]
	ds_read_b64_tr_b16 v[216:217], v152 offset:52576
	ds_read_b64_tr_b16 v[218:219], v152 offset:61280
	s_nop 2
	s_waitcnt lgkmcnt(10)
	s_nop 0
	s_nop 0
	v_mfma_f32_16x16x32_bf16 v[46:49], v[240:243], v[74:77], v[54:57]
	ds_read_b64_tr_b16 v[220:221], v152 offset:52608
	ds_read_b64_tr_b16 v[222:223], v152 offset:61312
	s_nop 2
	s_waitcnt lgkmcnt(10)
	s_nop 0
	s_nop 0
	v_mfma_f32_16x16x32_bf16 v[50:53], v[244:247], v[74:77], v[58:61]
	ds_read_b64_tr_b16 v[224:225], v152 offset:52640
	ds_read_b64_tr_b16 v[226:227], v152 offset:61344
	s_nop 2
	s_waitcnt lgkmcnt(10)
	s_nop 0
	s_nop 0
	v_mfma_f32_16x16x32_bf16 v[30:33], v[204:207], v[74:77], v[30:33]
	ds_read_b64_tr_b16 v[228:229], v152 offset:52672
	ds_read_b64_tr_b16 v[230:231], v152 offset:61376
	s_waitcnt lgkmcnt(10)
	v_mfma_f32_16x16x32_bf16 v[26:29], v[208:211], v[74:77], v[26:29]
	ds_read_b64_tr_b16 v[232:233], v152 offset:52448
	ds_read_b64_tr_b16 v[234:235], v152 offset:61152
	s_waitcnt lgkmcnt(10)
	v_mfma_f32_16x16x32_bf16 v[22:25], v[212:215], v[74:77], v[22:25]
	ds_read_b64_tr_b16 v[236:237], v152 offset:52704
	ds_read_b64_tr_b16 v[238:239], v152 offset:61408
	s_waitcnt lgkmcnt(10)
	v_mfma_f32_16x16x32_bf16 v[18:21], v[216:219], v[74:77], v[18:21]
	s_waitcnt lgkmcnt(8)
	s_nop 0
	s_nop 0
	v_mfma_f32_16x16x32_bf16 v[14:17], v[220:223], v[74:77], v[14:17]
	s_waitcnt lgkmcnt(6)
	s_nop 0
	s_nop 0
	v_mfma_f32_16x16x32_bf16 v[10:13], v[224:227], v[74:77], v[10:13]
	s_waitcnt lgkmcnt(4)
	s_nop 0
	s_nop 0
	v_mfma_f32_16x16x32_bf16 v[58:61], v[228:231], v[74:77], v[66:69]
	s_nop 2
	ds_bpermute_b32 v66, v151, v82
	s_waitcnt lgkmcnt(0)
	v_add_f32_e32 v66, v82, v66
	ds_bpermute_b32 v67, v147, v66
	v_mfma_f32_16x16x32_bf16 v[54:57], v[232:235], v[74:77], v[62:65]
	s_nop 2
	s_waitcnt lgkmcnt(0)
; __device__ __forceinline__ unsigned cvtpk(float lo, float hi) { unsigned r; asm volatile("v_cvt_pk_bf16_f32 %0, %1, %2" : "=v"(r) : "v"(lo), "v"(hi)); return r; }
; __device__ __forceinline__ void phase_xattn(CArgs& A, int l, unsigned char* lds, int tid) {
;     ...
;     for (int it = blockIdx.x; it < BATCH * 4 * 16; it += gridDim.x) {
;     ...
;         float ltot = lsum + __shfl_xor(lsum, 16); ltot += __shfl_xor(ltot, 32);
;         const float inv = 1.f / ltot;
;         bf16* op = O + row * DM + h * 256 + 4 * g;
; #pragma unroll
;         for (int db = 0; db < 16; ++db) { u32x2 w; w.x = cvtpk(o[db][0] * inv, o[db][1] * inv); w.y = cvtpk(o[db][2] * inv, o[db][3] * inv); *(u32x2*)(op + db * 16) = w; }
;     }
	s_nop 0
	s_nop 0
	v_add_f32_e32 v66, v66, v67
	v_div_scale_f32 v67, s[0:1], v66, v66, 1.0
	v_rcp_f32_e32 v68, v67
	s_nop 0
	v_mfma_f32_16x16x32_bf16 v[62:65], v[236:239], v[74:77], v[70:73]
	v_readlane_b32 s0, v251, 6
	v_readlane_b32 s1, v251, 7
	v_fma_f32 v69, -v67, v68, 1.0
	v_fmac_f32_e32 v68, v69, v68
	v_div_scale_f32 v69, vcc, 1.0, v66, 1.0
	v_mul_f32_e32 v70, v69, v68
	v_fma_f32 v71, -v67, v70, v69
	v_fmac_f32_e32 v70, v71, v68
	v_fma_f32 v67, -v67, v70, v69
	v_div_fmas_f32 v67, v67, v68, v70
	v_div_fixup_f32 v70, v67, v66, 1.0
	v_lshl_add_u64 v[66:67], s[6:7], 0, v[144:145]
	v_lshl_add_u64 v[66:67], v[66:67], 0, s[14:15]
	v_lshlrev_b32_e32 v68, 1, v143
	v_mov_b32_e32 v69, v0
	v_lshl_add_u64 v[66:67], v[66:67], 0, v[68:69]
	v_and_b32_e32 v68, 16, v167
	v_lshrrev_b32_e32 v69, 1, v68
	v_add_u32_e32 v68, v68, v69
	v_mov_b32_e32 v69, v0
	v_lshl_add_u64 v[66:67], v[66:67], 0, v[68:69]
	v_mul_f32_e32 v68, v2, v70
	v_mul_f32_e32 v69, v3, v70
	v_cvt_pk_bf16_f32 v240, v68, v69
	v_mul_f32_e32 v68, v4, v70
	v_mul_f32_e32 v69, v5, v70
	v_cvt_pk_bf16_f32 v241, v68, v69
	v_mul_f32_e32 v68, v6, v70
	v_mul_f32_e32 v69, v7, v70
	v_cvt_pk_bf16_f32 v242, v68, v69
	v_mul_f32_e32 v68, v8, v70
	v_mul_f32_e32 v69, v9, v70
	v_cvt_pk_bf16_f32 v243, v68, v69
	s_nop 1
	v_permlane16_swap_b32_e32 v240, v242
	v_permlane16_swap_b32_e32 v241, v243
	global_store_dwordx4 v[66:67], v[240:243], off
	v_mul_f32_e32 v68, v34, v70
	v_mul_f32_e32 v69, v35, v70
	v_cvt_pk_bf16_f32 v244, v68, v69
	v_mul_f32_e32 v68, v36, v70
	v_mul_f32_e32 v69, v37, v70
	v_cvt_pk_bf16_f32 v245, v68, v69
	v_mul_f32_e32 v68, v38, v70
	v_mul_f32_e32 v69, v39, v70
	v_cvt_pk_bf16_f32 v246, v68, v69
	v_mul_f32_e32 v68, v40, v70
	v_mul_f32_e32 v69, v41, v70
	v_cvt_pk_bf16_f32 v247, v68, v69
	s_nop 1
	v_permlane16_swap_b32_e32 v244, v246
	v_permlane16_swap_b32_e32 v245, v247
	global_store_dwordx4 v[66:67], v[244:247], off offset:64
	v_mul_f32_e32 v68, v42, v70
	v_mul_f32_e32 v69, v43, v70
	v_cvt_pk_bf16_f32 v240, v68, v69
	v_mul_f32_e32 v68, v44, v70
	v_mul_f32_e32 v69, v45, v70
	v_cvt_pk_bf16_f32 v241, v68, v69
	v_mul_f32_e32 v68, v46, v70
	v_mul_f32_e32 v69, v47, v70
	v_cvt_pk_bf16_f32 v242, v68, v69
	v_mul_f32_e32 v68, v48, v70
	v_mul_f32_e32 v69, v49, v70
	v_cvt_pk_bf16_f32 v243, v68, v69
	s_nop 1
	v_permlane16_swap_b32_e32 v240, v242
	v_permlane16_swap_b32_e32 v241, v243
	global_store_dwordx4 v[66:67], v[240:243], off offset:128
	v_mul_f32_e32 v68, v50, v70
	v_mul_f32_e32 v69, v51, v70
	v_cvt_pk_bf16_f32 v244, v68, v69
	v_mul_f32_e32 v68, v52, v70
	v_mul_f32_e32 v69, v53, v70
	v_cvt_pk_bf16_f32 v245, v68, v69
	v_mul_f32_e32 v68, v54, v70
	v_mul_f32_e32 v69, v55, v70
	v_cvt_pk_bf16_f32 v246, v68, v69
	v_mul_f32_e32 v68, v56, v70
	v_mul_f32_e32 v69, v57, v70
	v_cvt_pk_bf16_f32 v247, v68, v69
	s_nop 1
	v_permlane16_swap_b32_e32 v244, v246
	v_permlane16_swap_b32_e32 v245, v247
	global_store_dwordx4 v[66:67], v[244:247], off offset:192
	v_mul_f32_e32 v68, v30, v70
	v_mul_f32_e32 v69, v31, v70
	v_cvt_pk_bf16_f32 v240, v68, v69
	v_mul_f32_e32 v68, v32, v70
	v_mul_f32_e32 v69, v33, v70
	v_cvt_pk_bf16_f32 v241, v68, v69
	v_mul_f32_e32 v68, v26, v70
	v_mul_f32_e32 v69, v27, v70
	v_cvt_pk_bf16_f32 v242, v68, v69
	v_mul_f32_e32 v68, v28, v70
	v_mul_f32_e32 v69, v29, v70
	v_cvt_pk_bf16_f32 v243, v68, v69
	s_nop 1
	v_permlane16_swap_b32_e32 v240, v242
	v_permlane16_swap_b32_e32 v241, v243
	global_store_dwordx4 v[66:67], v[240:243], off offset:256
	v_mul_f32_e32 v68, v22, v70
	v_mul_f32_e32 v69, v23, v70
	v_cvt_pk_bf16_f32 v244, v68, v69
	v_mul_f32_e32 v68, v24, v70
	v_mul_f32_e32 v69, v25, v70
	v_cvt_pk_bf16_f32 v245, v68, v69
	v_mul_f32_e32 v68, v18, v70
	v_mul_f32_e32 v69, v19, v70
	v_cvt_pk_bf16_f32 v246, v68, v69
	v_mul_f32_e32 v68, v20, v70
	v_mul_f32_e32 v69, v21, v70
	v_cvt_pk_bf16_f32 v247, v68, v69
	s_nop 1
	v_permlane16_swap_b32_e32 v244, v246
	v_permlane16_swap_b32_e32 v245, v247
	global_store_dwordx4 v[66:67], v[244:247], off offset:320
	v_mul_f32_e32 v68, v14, v70
	v_mul_f32_e32 v69, v15, v70
	v_cvt_pk_bf16_f32 v240, v68, v69
	v_mul_f32_e32 v68, v16, v70
	v_mul_f32_e32 v69, v17, v70
	v_cvt_pk_bf16_f32 v241, v68, v69
	v_mul_f32_e32 v68, v10, v70
	v_mul_f32_e32 v69, v11, v70
	v_cvt_pk_bf16_f32 v242, v68, v69
	v_mul_f32_e32 v68, v12, v70
	v_mul_f32_e32 v69, v13, v70
	v_cvt_pk_bf16_f32 v243, v68, v69
	s_nop 1
	v_permlane16_swap_b32_e32 v240, v242
	v_permlane16_swap_b32_e32 v241, v243
	global_store_dwordx4 v[66:67], v[240:243], off offset:384
	v_mul_f32_e32 v68, v58, v70
	v_mul_f32_e32 v69, v59, v70
	v_cvt_pk_bf16_f32 v244, v68, v69
	v_mul_f32_e32 v68, v60, v70
	v_mul_f32_e32 v69, v61, v70
	v_cvt_pk_bf16_f32 v245, v68, v69
	v_mul_f32_e32 v68, v62, v70
	v_mul_f32_e32 v69, v63, v70
	v_cvt_pk_bf16_f32 v246, v68, v69
	v_mul_f32_e32 v68, v64, v70
	v_mul_f32_e32 v69, v65, v70
	v_cvt_pk_bf16_f32 v247, v68, v69
	s_nop 1
	v_permlane16_swap_b32_e32 v244, v246
	v_permlane16_swap_b32_e32 v245, v247
	global_store_dwordx4 v[66:67], v[244:247], off offset:448
	s_load_dword s0, s[0:1], 0x0
	s_waitcnt lgkmcnt(0)
	s_add_i32 s11, s0, s11
	s_cmpk_gt_i32 s11, 0x3ff
	s_cbranch_scc0 .LBB0_144
